# row-wise N2/P0 loops: ring copies that read the freshly loaded (two-rows-ahead) registers moved to the iteration end behind one counted vmcnt; early waits dropped
# baseline (speedup 1.0000x reference)
; __device__ __forceinline__ int tidx() { int t = threadIdx.x & 255; asm volatile("" : "+v"(t)); return t; }
; __device__ __forceinline__ void rowwise_phase(CP p, int mode, const float* wpost, const float* wpre, bool write_hn, int nparts) {
;   const int tid_ = tidx(); const int lane = tid_ & 63, gw = bidx() * 4 + (tid_ >> 6), nw = nvb() * 4;
;   const float* tmp = (const float*)(p.ws + WS_TMP);
;   bf16_t* hn = (bf16_t*)(p.ws + WS_Y);
;   float4 wpo[4], wpr[4];
; #pragma unroll
;   for (int q = 0; q < 4; ++q) {
;     wpo[q] = (mode != 0) ? *reinterpret_cast<const float4*>(wpost + q * 256 + lane * 4) : make_float4(0.f, 0.f, 0.f, 0.f);
;     wpr[q] = write_hn ? *reinterpret_cast<const float4*>(wpre + q * 256 + lane * 4) : make_float4(0.f, 0.f, 0.f, 0.f);
;   }
;   float4 tv[4], hv[4], tvn[4], hvn[4], tvm[4], hvm[4];
;   auto loadrow = [&](int row, float4 (&t)[4], float4 (&h)[4]) {
;     if (mode == 0) {
;       const float* src = row < RREAL ? p.in[0] + (size_t)row * D : p.in[1] + (size_t)((row - RREAL) & 15) * D;
; #pragma unroll
;       for (int q = 0; q < 4; ++q) { h[q] = *reinterpret_cast<const float4*>(src + q * 256 + lane * 4); t[q] = make_float4(0.f, 0.f, 0.f, 0.f); }
;     } else {
;       const float* hr = hrow_ptr(p, row);
; #pragma unroll
;       for (int q = 0; q < 4; ++q) {
;         if (row < RREAL) {
;           {
;             const float* tp_ = tmp + (size_t)row * D + q * 256 + lane * 4;
;             t[q] = make_float4(__builtin_nontemporal_load(tp_), __builtin_nontemporal_load(tp_ + 1), __builtin_nontemporal_load(tp_ + 2), __builtin_nontemporal_load(tp_ + 3));
;           }
;         } else {
;           const float* pp = (const float*)(p.ws + WS_PART) + (size_t)(row - RREAL) * D + q * 256 + lane * 4;
;           float4 a = *reinterpret_cast<const float4*>(pp);
;           for (int kc = 1; kc < nparts; ++kc) {
;             const float4 c = *reinterpret_cast<const float4*>(pp + (size_t)kc * 128 * 1024);
;             a.x += c.x; a.y += c.y; a.z += c.z; a.w += c.w;
;           }
;           t[q] = a;
;         }
;         h[q] = *reinterpret_cast<const float4*>(hr + q * 256 + lane * 4);
;       }
;     }
;   };
;   if (gw < R) loadrow(gw, tv, hv);
;   if (gw + nw < R) loadrow(gw + nw, tvn, hvn);
;   for (int row = gw; row < R; row += nw) {
.LBB0_898:
	s_or_b64 exec, exec, s[44:45]
	s_and_saveexec_b64 s[12:13], s[38:39]
	s_cbranch_execz .LBB0_931
	v_readlane_b32 s0, v253, 63
	v_readlane_b32 s1, v254, 0
	s_load_dwordx2 s[44:45], s[0:1], 0x120
	v_lshl_add_u64 v[98:99], s[92:93], 0, v[148:149]
	s_mov_b64 s[0:1], 0xded0800
	v_and_b32_e32 v97, 64, v217
	v_lshl_add_u64 v[130:131], v[98:99], 0, s[0:1]
	v_add_u32_e32 v97, 64, v97
	v_xor_b32_e32 v98, 32, v217
	v_cmp_lt_i32_e32 vcc, v98, v97
	v_readlane_b32 s0, v254, 1
	v_and_b32_e32 v96, 63, v96
	v_cndmask_b32_e32 v98, v217, v98, vcc
	v_lshlrev_b32_e32 v138, 2, v98
	v_xor_b32_e32 v98, 16, v217
	v_cmp_lt_i32_e32 vcc, v98, v97
	v_readlane_b32 s1, v254, 2
	s_add_u32 s4, s92, 0x4000
	v_cndmask_b32_e32 v98, v217, v98, vcc
	v_lshlrev_b32_e32 v139, 2, v98
	v_xor_b32_e32 v98, 8, v217
	v_cmp_lt_i32_e32 vcc, v98, v97
	v_lshl_add_u64 v[132:133], s[0:1], 0, v[148:149]
	s_mov_b64 s[0:1], 0x7a90e04
	v_cndmask_b32_e32 v98, v217, v98, vcc
	v_lshlrev_b32_e32 v140, 2, v98
	v_xor_b32_e32 v98, 4, v217
	v_cmp_lt_i32_e32 vcc, v98, v97
	s_addc_u32 s5, s93, 0
	s_mov_b64 s[48:49], 0
	v_cndmask_b32_e32 v98, v217, v98, vcc
	v_lshlrev_b32_e32 v141, 2, v98
	v_xor_b32_e32 v98, 2, v217
	v_cmp_lt_i32_e32 vcc, v98, v97
	s_mov_b64 s[50:51], 0
	v_mov_b32_e32 v144, v128
	v_cndmask_b32_e32 v98, v217, v98, vcc
	v_lshlrev_b32_e32 v142, 2, v98
	v_xor_b32_e32 v98, 1, v217
	v_cmp_lt_i32_e32 vcc, v98, v97
	s_nop 1
	v_cndmask_b32_e32 v97, v217, v98, vcc
	v_lshlrev_b64 v[98:99], 11, v[128:129]
	v_lshl_or_b32 v98, v96, 3, v98
	v_lshlrev_b32_e32 v143, 2, v97
	v_lshl_add_u64 v[96:97], s[92:93], 0, v[98:99]
	v_lshl_add_u64 v[134:135], v[96:97], 0, s[0:1]
	s_waitcnt vmcnt(0)
	s_branch .LBB0_902

; __device__ __forceinline__ void rowwise_phase(CP p, int mode, const float* wpost, const float* wpre, bool write_hn, int nparts) {
;     ...
;     if (mode != 0) {
;       float ss = 0.f;
; #pragma unroll
;       for (int q = 0; q < 4; ++q) ss += tv[q].x * tv[q].x + tv[q].y * tv[q].y + tv[q].z * tv[q].z + tv[q].w * tv[q].w;
;       ss = wave_sum(ss);
;       const float rs = rsqrtf(ss * (1.f / D) + EPS);
; #pragma unroll
;       for (int q = 0; q < 4; ++q) {
;         hv[q].x += tv[q].x * rs * wpo[q].x;
;         hv[q].y += tv[q].y * rs * wpo[q].y;
;         hv[q].z += tv[q].z * rs * wpo[q].z;
;         hv[q].w += tv[q].w * rs * wpo[q].w;
;       }
;     }
; #pragma unroll
;     for (int q = 0; q < 4; ++q) {
;       float* hp_ = hr + q * 256 + lane * 4;
;       __builtin_nontemporal_store(hv[q].x, hp_); __builtin_nontemporal_store(hv[q].y, hp_ + 1);
;       __builtin_nontemporal_store(hv[q].z, hp_ + 2); __builtin_nontemporal_store(hv[q].w, hp_ + 3);
;     }
;     if (write_hn) {
;       float ss = 0.f;
; #pragma unroll
;       for (int q = 0; q < 4; ++q) ss += hv[q].x * hv[q].x + hv[q].y * hv[q].y + hv[q].z * hv[q].z + hv[q].w * hv[q].w;
;       ss = wave_sum(ss);
;       const float rs = rsqrtf(ss * (1.f / D) + EPS);
.LBB0_901:
	s_or_b64 exec, exec, s[42:43]
	v_mov_b32_e32 v136, v40
	v_mov_b32_e32 v137, v32
	v_pk_mul_f32 v[136:137], v[136:137], v[136:137]
	v_mov_b32_e32 v146, v41
	v_mov_b32_e32 v147, v33
	v_pk_fma_f32 v[136:137], v[146:147], v[146:147], v[136:137]
	v_mov_b32_e32 v146, v42
	v_mov_b32_e32 v147, v34
	v_pk_fma_f32 v[136:137], v[146:147], v[146:147], v[136:137]
	v_mov_b32_e32 v146, v43
	v_mov_b32_e32 v147, v35
	v_pk_fma_f32 v[136:137], v[146:147], v[146:147], v[136:137]
	v_mov_b32_e32 v146, v56
	v_mov_b32_e32 v147, v48
	v_pk_mul_f32 v[146:147], v[146:147], v[146:147]
	v_mov_b32_e32 v152, v57
	v_mov_b32_e32 v153, v49
	v_pk_fma_f32 v[146:147], v[152:153], v[152:153], v[146:147]
	v_mov_b32_e32 v152, v58
	v_mov_b32_e32 v153, v50
	v_pk_fma_f32 v[146:147], v[152:153], v[152:153], v[146:147]
	v_mov_b32_e32 v152, v59
	v_mov_b32_e32 v153, v51
	v_pk_fma_f32 v[146:147], v[152:153], v[152:153], v[146:147]
	v_add_f32_e32 v136, v136, v137
	v_add_f32_e32 v136, v147, v136
	v_add_f32_e32 v136, v146, v136
	ds_bpermute_b32 v137, v138, v136
	s_movk_i32 s0, 0x4000
	s_waitcnt lgkmcnt(0)
	v_add_f32_e32 v136, v136, v137
	ds_bpermute_b32 v137, v139, v136
	s_waitcnt lgkmcnt(0)
	v_add_f32_e32 v136, v136, v137
	ds_bpermute_b32 v137, v140, v136
	s_waitcnt lgkmcnt(0)
	v_add_f32_e32 v136, v136, v137
	ds_bpermute_b32 v137, v141, v136
	s_waitcnt lgkmcnt(0)
	v_add_f32_e32 v136, v136, v137
	ds_bpermute_b32 v137, v142, v136
	s_waitcnt lgkmcnt(0)
	v_add_f32_e32 v136, v136, v137
	ds_bpermute_b32 v137, v143, v136
	s_waitcnt lgkmcnt(0)
	v_add_f32_e32 v136, v136, v137
	v_fmamk_f32 v136, v136, 0x3a800000, v215
	v_mul_f32_e32 v137, 0x4b800000, v136
	v_cmp_gt_f32_e32 vcc, s33, v136
	s_nop 1
	v_cndmask_b32_e32 v136, v136, v137, vcc
	v_rsq_f32_e32 v136, v136
	s_nop 0
	v_mul_f32_e32 v137, 0x45800000, v136
	v_cndmask_b32_e32 v136, v136, v137, vcc
	v_pk_mul_f32 v[32:33], v[32:33], v[136:137] op_sel_hi:[1,0]
	v_pk_mul_f32 v[40:41], v[40:41], v[136:137] op_sel_hi:[1,0]
	v_pk_mul_f32 v[34:35], v[34:35], v[136:137] op_sel_hi:[1,0]
	v_pk_mul_f32 v[42:43], v[42:43], v[136:137] op_sel_hi:[1,0]
	v_pk_fma_f32 v[32:33], v[0:1], v[32:33], v[36:37]
	v_pk_fma_f32 v[36:37], v[4:5], v[40:41], v[44:45]
	v_pk_mul_f32 v[48:49], v[48:49], v[136:137] op_sel_hi:[1,0]
	v_pk_fma_f32 v[34:35], v[2:3], v[34:35], v[38:39]
	v_pk_fma_f32 v[38:39], v[6:7], v[42:43], v[46:47]
	v_pk_mul_f32 v[42:43], v[50:51], v[136:137] op_sel_hi:[1,0]
	v_mov_b32_e32 v50, v33
	v_mov_b32_e32 v51, v37
	v_pk_fma_f32 v[40:41], v[16:17], v[48:49], v[52:53]
	v_pk_mul_f32 v[44:45], v[56:57], v[136:137] op_sel_hi:[1,0]
	v_mov_b32_e32 v48, v32
	v_mov_b32_e32 v49, v36
	v_pk_mul_f32 v[50:51], v[50:51], v[50:51]
	v_pk_fma_f32 v[44:45], v[20:21], v[44:45], v[60:61]
	v_pk_fma_f32 v[48:49], v[48:49], v[48:49], v[50:51]
	v_mov_b32_e32 v50, v34
	v_mov_b32_e32 v51, v38
	v_pk_mul_f32 v[46:47], v[58:59], v[136:137] op_sel_hi:[1,0]
	v_pk_fma_f32 v[48:49], v[50:51], v[50:51], v[48:49]
	v_mov_b32_e32 v50, v35
	v_mov_b32_e32 v51, v39
	v_mov_b32_e32 v52, v45
	v_mov_b32_e32 v53, v41
	v_pk_fma_f32 v[42:43], v[18:19], v[42:43], v[54:55]
	v_pk_fma_f32 v[46:47], v[22:23], v[46:47], v[62:63]
	v_pk_fma_f32 v[48:49], v[50:51], v[50:51], v[48:49]
	v_mov_b32_e32 v50, v44
	v_mov_b32_e32 v51, v40
	v_pk_mul_f32 v[52:53], v[52:53], v[52:53]
	v_add_f32_e32 v48, v48, v49
	v_pk_fma_f32 v[50:51], v[50:51], v[50:51], v[52:53]
	v_mov_b32_e32 v52, v46
	v_mov_b32_e32 v53, v42
	v_pk_fma_f32 v[50:51], v[52:53], v[52:53], v[50:51]
	v_mov_b32_e32 v52, v47
	v_mov_b32_e32 v53, v43
	v_pk_fma_f32 v[50:51], v[52:53], v[52:53], v[50:51]
	v_add_u32_e32 v52, 0xffffc000, v144
	v_add_f32_e32 v48, v51, v48
	v_add_f32_e32 v48, v50, v48
	ds_bpermute_b32 v49, v138, v48
	v_cmp_gt_i32_e32 vcc, s0, v144
	v_mov_b32_e32 v53, s45
	v_add_u32_e32 v144, s60, v144
	v_mov_b64_e32 v[60:61], v[92:93]
	s_waitcnt lgkmcnt(0)
	v_add_f32_e32 v48, v48, v49
	ds_bpermute_b32 v49, v139, v48
	v_mov_b64_e32 v[56:57], v[88:89]
	v_mov_b64_e32 v[62:63], v[94:95]
	s_waitcnt lgkmcnt(0)
; __device__ __forceinline__ void rowwise_phase(CP p, int mode, const float* wpost, const float* wpre, bool write_hn, int nparts) {
;     ...
; #pragma unroll
;     for (int q = 0; q < 4; ++q) {
;       float* hp_ = hr + q * 256 + lane * 4;
;       __builtin_nontemporal_store(hv[q].x, hp_); __builtin_nontemporal_store(hv[q].y, hp_ + 1);
;       __builtin_nontemporal_store(hv[q].z, hp_ + 2); __builtin_nontemporal_store(hv[q].w, hp_ + 3);
;     }
;     if (write_hn) {
;       float ss = 0.f;
; #pragma unroll
;       for (int q = 0; q < 4; ++q) ss += hv[q].x * hv[q].x + hv[q].y * hv[q].y + hv[q].z * hv[q].z + hv[q].w * hv[q].w;
;       ss = wave_sum(ss);
;       const float rs = rsqrtf(ss * (1.f / D) + EPS);
; #pragma unroll
;       for (int q = 0; q < 4; ++q) {
;         uint2 o;
;         o.x = pack2(hv[q].x * rs * wpr[q].x, hv[q].y * rs * wpr[q].y);
;         o.y = pack2(hv[q].z * rs * wpr[q].z, hv[q].w * rs * wpr[q].w);
;         *reinterpret_cast<uint2*>(hn + (size_t)row * D + q * 256 + lane * 4) = o;
;       }
;     }
; #pragma unroll
;     for (int q = 0; q < 4; ++q) { tv[q] = tvn[q]; hv[q] = hvn[q]; tvn[q] = tvm[q]; hvn[q] = hvm[q]; }
	v_add_f32_e32 v50, v48, v49
	ds_bpermute_b32 v51, v140, v50
	v_lshl_add_u64 v[48:49], v[128:129], 0, s[50:51]
	v_cndmask_b32_e32 v48, v52, v48, vcc
	v_mov_b32_e32 v52, s5
	v_cndmask_b32_e32 v49, 0, v49, vcc
	s_waitcnt lgkmcnt(0)
	v_add_f32_e32 v50, v50, v51
	ds_bpermute_b32 v51, v141, v50
	v_lshlrev_b64 v[48:49], 12, v[48:49]
	s_add_u32 s50, s50, s60
	s_addc_u32 s51, s51, s61
	s_waitcnt lgkmcnt(0)
	v_add_f32_e32 v54, v50, v51
	ds_bpermute_b32 v55, v142, v54
	v_cndmask_b32_e32 v51, v52, v53, vcc
	v_mov_b32_e32 v50, s4
	v_mov_b32_e32 v52, s44
	v_cndmask_b32_e32 v50, v50, v52, vcc
	s_waitcnt lgkmcnt(0)
	v_add_f32_e32 v52, v54, v55
	ds_bpermute_b32 v53, v143, v52
	v_lshl_add_u64 v[48:49], v[50:51], 0, v[48:49]
	v_lshl_add_u64 v[48:49], v[48:49], 0, v[148:149]
	global_store_dwordx4 v[48:49], v[32:35], off nt
	global_store_dwordx4 v[48:49], v[36:39], off offset:1024 nt
	global_store_dwordx4 v[48:49], v[40:43], off offset:2048 nt
	global_store_dwordx4 v[48:49], v[44:47], off offset:3072 nt
	s_waitcnt lgkmcnt(0)
	v_add_f32_e32 v50, v52, v53
	v_fmamk_f32 v50, v50, 0x3a800000, v215
	v_mul_f32_e32 v51, 0x4b800000, v50
	v_cmp_gt_f32_e32 vcc, s33, v50
	v_mov_b64_e32 v[52:53], v[84:85]
	v_cndmask_b32_e32 v50, v50, v51, vcc
	v_rsq_f32_e32 v50, v50
	v_mov_b64_e32 v[54:55], v[86:87]
	v_mov_b64_e32 v[58:59], v[90:91]
	v_mul_f32_e32 v48, 0x45800000, v50
	v_cndmask_b32_e32 v48, v50, v48, vcc
	v_pk_mul_f32 v[32:33], v[32:33], v[48:49] op_sel_hi:[1,0]
	v_pk_mul_f32 v[34:35], v[34:35], v[48:49] op_sel_hi:[1,0]
	v_pk_mul_f32 v[32:33], v[8:9], v[32:33]
	v_pk_mul_f32 v[34:35], v[10:11], v[34:35]
	v_cvt_pk_bf16_f32 v32, v32, v33
	v_cvt_pk_bf16_f32 v33, v34, v35
	global_store_dwordx2 v[134:135], v[32:33], off offset:-1540
	v_pk_mul_f32 v[32:33], v[36:37], v[48:49] op_sel_hi:[1,0]
	v_pk_mul_f32 v[34:35], v[38:39], v[48:49] op_sel_hi:[1,0]
	v_pk_mul_f32 v[32:33], v[12:13], v[32:33]
	v_pk_mul_f32 v[34:35], v[14:15], v[34:35]
	v_cvt_pk_bf16_f32 v32, v32, v33
	v_cvt_pk_bf16_f32 v33, v34, v35
	global_store_dwordx2 v[134:135], v[32:33], off offset:-1028
	v_pk_mul_f32 v[32:33], v[40:41], v[48:49] op_sel_hi:[1,0]
	v_pk_mul_f32 v[34:35], v[42:43], v[48:49] op_sel_hi:[1,0]
	v_pk_mul_f32 v[32:33], v[24:25], v[32:33]
	v_pk_mul_f32 v[34:35], v[26:27], v[34:35]
	v_cvt_pk_bf16_f32 v32, v32, v33
	v_cvt_pk_bf16_f32 v33, v34, v35
	global_store_dwordx2 v[134:135], v[32:33], off offset:-516
	v_pk_mul_f32 v[32:33], v[44:45], v[48:49] op_sel_hi:[1,0]
	v_pk_mul_f32 v[34:35], v[46:47], v[48:49] op_sel_hi:[1,0]
	v_pk_mul_f32 v[32:33], v[28:29], v[32:33]
	v_pk_mul_f32 v[34:35], v[30:31], v[34:35]
	v_cvt_pk_bf16_f32 v32, v32, v33
	v_cvt_pk_bf16_f32 v33, v34, v35
	v_cmp_lt_i32_e32 vcc, s67, v144
	global_store_dwordx2 v[134:135], v[32:33], off offset:-4
	v_lshl_add_u64 v[134:135], v[134:135], 0, s[8:9]
	s_or_b64 s[48:49], vcc, s[48:49]
	v_mov_b64_e32 v[36:37], v[68:69]
	v_mov_b64_e32 v[32:33], v[64:65]
	v_mov_b64_e32 v[38:39], v[70:71]
	v_mov_b64_e32 v[34:35], v[66:67]
	v_mov_b64_e32 v[44:45], v[76:77]
	v_mov_b64_e32 v[40:41], v[72:73]
	v_mov_b64_e32 v[46:47], v[78:79]
	v_mov_b64_e32 v[42:43], v[74:75]
	v_mov_b64_e32 v[48:49], v[80:81]
	v_mov_b64_e32 v[50:51], v[82:83]
	s_waitcnt vmcnt(8)
	v_mov_b64_e32 v[92:93], v[124:125]
	v_mov_b64_e32 v[88:89], v[120:121]
	v_mov_b64_e32 v[94:95], v[126:127]
	v_mov_b64_e32 v[84:85], v[116:117]
	v_mov_b64_e32 v[86:87], v[118:119]
	v_mov_b64_e32 v[68:69], v[100:101]
	v_mov_b64_e32 v[64:65], v[96:97]
	v_mov_b64_e32 v[70:71], v[102:103]
	v_mov_b64_e32 v[66:67], v[98:99]
	v_mov_b64_e32 v[76:77], v[108:109]
	v_mov_b64_e32 v[72:73], v[104:105]
	v_mov_b64_e32 v[78:79], v[110:111]
	v_mov_b64_e32 v[74:75], v[106:107]
	v_mov_b64_e32 v[80:81], v[112:113]
	v_mov_b64_e32 v[82:83], v[114:115]
	v_mov_b64_e32 v[90:91], v[122:123]
	s_andn2_b64 exec, exec, s[48:49]
	s_cbranch_execz .LBB0_931
